# final rmsnorm tile body rewritten by hand: all 32 row loads of a tile in flight per thread, lane-contiguous 16-byte stores, gains loaded once; plus coalesced GEMM epilogue stores and K-loop barrier sh
# speedup vs baseline: 1.0092x; 1.0009x over previous
; #define LAS __attribute__((address_space(3)))
; __device__ __forceinline__ float bf_lo(unsigned w) { return __uint_as_float(w << 16); }
; __device__ __forceinline__ float bf_hi(unsigned w) { return __uint_as_float(w & 0xffff0000u); }
; __device__ __forceinline__ void final_tiles(LAS unsigned char* lds, const bf16* XB, const float* ss, const float* g, float* OF, int G, int bx, int tid) {
;     pg8::StaticOrder S; S.init(M, DM, G, bx, WGM_DN); pg8::Unit u;
;     const pg8::RsTable T = pg8::rs_prepass(lds + 131072, ss, S, tid);
;     for (int i = 0; S.next(i, u); ++i) {
;         const int k = u.pm == T.pm[0] ? 0 : (u.pm == T.pm[1] ? 1 : (u.pm == T.pm[2] ? 2 : 3));
; #pragma unroll 4
;         for (int q = 0; q < 16; ++q) {
;             const int c = tid + 512 * q, lr = c >> 5, row = u.pm * 256 + lr, col = u.pn * 256 + (c & 31) * 8;
;             const v4u w = *(const v4u*)(XB + (size_t)row * DM + col);
;             const float rs = T.tab[k * 256 + lr];
;             const f32x4 g0 = *(const f32x4*)(g + col), g1 = *(const f32x4*)(g + col + 4);
;             f32x4* o = (f32x4*)(OF + (size_t)row * DM + col);
;             o[0] = (f32x4){bf_lo(w.x) * rs * g0.x, bf_hi(w.x) * rs * g0.y, bf_lo(w.y) * rs * g0.z, bf_hi(w.y) * rs * g0.w};
;             o[1] = (f32x4){bf_lo(w.z) * rs * g1.x, bf_hi(w.z) * rs * g1.y, bf_lo(w.w) * rs * g1.z, bf_hi(w.w) * rs * g1.w};
.LBB0_651:
	s_cmp_eq_u32 s13, s12
	s_cselect_b32 s0, 0x200, s56
	s_cmp_lg_u32 s13, s11
	s_cselect_b32 s1, s0, 0x100
	s_cmp_lg_u32 s13, s10
	s_cselect_b32 s2, s1, 0
	v_lshl_or_b32 v2, s9, 8, v19
	v_ashrrev_i32_e32 v3, 31, v2
	s_lshl_b32 s2, s2, 2
	v_readlane_b32 s16, v252, 13
	v_lshl_add_u64 v[10:11], v[2:3], 1, s[6:7]
	s_add_i32 s2, s2, 0
	v_lshlrev_b64 v[2:3], 2, v[2:3]
	v_readlane_b32 s17, v252, 14
	s_mov_b32 s0, 0
	s_lshl_b32 s1, s13, 8
	s_add_i32 s2, s2, 0x21000
	v_lshl_add_u64 v[12:13], s[22:23], 0, v[2:3]
	v_lshl_add_u64 v[14:15], s[16:17], 0, v[2:3]
	v_readlane_b32 s18, v252, 15
	v_readlane_b32 s19, v252, 16
	v_mbcnt_lo_u32_b32 v20, -1, 0
	v_mbcnt_hi_u32_b32 v20, -1, v20
	v_readlane_b32 s24, v252, 37
	v_lshrrev_b32_e32 v21, 5, v20
	s_lshl_b32 s25, s24, 1
	v_and_b32_e32 v22, 31, v20
	v_add_u32_e32 v21, s25, v21
	v_lshlrev_b32_e32 v25, 4, v22
	v_lshlrev_b32_e32 v23, 12, v21
	v_lshl_add_u32 v23, v22, 3, v23
	v_lshlrev_b32_e32 v24, 13, v21
	v_lshl_add_u32 v24, v22, 4, v24
	v_lshl_add_u32 v26, v21, 2, s2
	s_lshl_b32 s25, s1, 12
	s_lshl_b32 s26, s9, 9
	s_add_u32 s25, s25, s26
	s_add_u32 s16, s6, s25
	s_addc_u32 s17, s7, 0
	v_readlane_b32 s18, v252, 13
	v_readlane_b32 s19, v252, 14
	s_lshl_b32 s25, s1, 13
	s_lshl_b32 s26, s9, 10
	s_add_u32 s25, s25, s26
	s_add_u32 s18, s18, s25
	s_addc_u32 s19, s19, 0
	s_add_u32 s20, s22, s26
	s_addc_u32 s21, s23, 0
	global_load_dwordx4 v[28:31], v25, s[20:21]
	global_load_dwordx4 v[32:35], v25, s[20:21] offset:512
	global_load_dwordx2 v[52:53], v23, s[16:17]
	global_load_dwordx2 v[54:55], v23, s[16:17] offset:256
	s_add_u32 s16, s16, 0x10000
	s_addc_u32 s17, s17, 0
	global_load_dwordx2 v[56:57], v23, s[16:17]
	global_load_dwordx2 v[58:59], v23, s[16:17] offset:256
	s_add_u32 s16, s16, 0x10000
	s_addc_u32 s17, s17, 0
	global_load_dwordx2 v[60:61], v23, s[16:17]
	global_load_dwordx2 v[62:63], v23, s[16:17] offset:256
	s_add_u32 s16, s16, 0x10000
	s_addc_u32 s17, s17, 0
	global_load_dwordx2 v[64:65], v23, s[16:17]
	global_load_dwordx2 v[66:67], v23, s[16:17] offset:256
	s_add_u32 s16, s16, 0x10000
	s_addc_u32 s17, s17, 0
	global_load_dwordx2 v[68:69], v23, s[16:17]
	global_load_dwordx2 v[70:71], v23, s[16:17] offset:256
	s_add_u32 s16, s16, 0x10000
	s_addc_u32 s17, s17, 0
	global_load_dwordx2 v[72:73], v23, s[16:17]
	global_load_dwordx2 v[74:75], v23, s[16:17] offset:256
	s_add_u32 s16, s16, 0x10000
	s_addc_u32 s17, s17, 0
	global_load_dwordx2 v[76:77], v23, s[16:17]
	global_load_dwordx2 v[78:79], v23, s[16:17] offset:256
	s_add_u32 s16, s16, 0x10000
	s_addc_u32 s17, s17, 0
	global_load_dwordx2 v[80:81], v23, s[16:17]
	global_load_dwordx2 v[82:83], v23, s[16:17] offset:256
	s_add_u32 s16, s16, 0x10000
	s_addc_u32 s17, s17, 0
	global_load_dwordx2 v[84:85], v23, s[16:17]
	global_load_dwordx2 v[86:87], v23, s[16:17] offset:256
	s_add_u32 s16, s16, 0x10000
	s_addc_u32 s17, s17, 0
	global_load_dwordx2 v[88:89], v23, s[16:17]
	global_load_dwordx2 v[90:91], v23, s[16:17] offset:256
	s_add_u32 s16, s16, 0x10000
	s_addc_u32 s17, s17, 0
	global_load_dwordx2 v[92:93], v23, s[16:17]
	global_load_dwordx2 v[94:95], v23, s[16:17] offset:256
	s_add_u32 s16, s16, 0x10000
	s_addc_u32 s17, s17, 0
	global_load_dwordx2 v[96:97], v23, s[16:17]
	global_load_dwordx2 v[98:99], v23, s[16:17] offset:256
	s_add_u32 s16, s16, 0x10000
	s_addc_u32 s17, s17, 0
	global_load_dwordx2 v[100:101], v23, s[16:17]
	global_load_dwordx2 v[102:103], v23, s[16:17] offset:256
	s_add_u32 s16, s16, 0x10000
	s_addc_u32 s17, s17, 0
	global_load_dwordx2 v[104:105], v23, s[16:17]
	global_load_dwordx2 v[106:107], v23, s[16:17] offset:256
	s_add_u32 s16, s16, 0x10000
	s_addc_u32 s17, s17, 0
	global_load_dwordx2 v[108:109], v23, s[16:17]
	global_load_dwordx2 v[110:111], v23, s[16:17] offset:256
	s_add_u32 s16, s16, 0x10000
	s_addc_u32 s17, s17, 0
	global_load_dwordx2 v[112:113], v23, s[16:17]
	global_load_dwordx2 v[114:115], v23, s[16:17] offset:256
	ds_read_b32 v36, v26
	ds_read_b32 v37, v26 offset:64
	ds_read_b32 v38, v26 offset:128
	ds_read_b32 v39, v26 offset:192
	ds_read_b32 v40, v26 offset:256
	ds_read_b32 v41, v26 offset:320
	ds_read_b32 v42, v26 offset:384
	ds_read_b32 v43, v26 offset:448
	ds_read_b32 v44, v26 offset:512
	ds_read_b32 v45, v26 offset:576
	ds_read_b32 v46, v26 offset:640
	ds_read_b32 v47, v26 offset:704
	ds_read_b32 v48, v26 offset:768
	ds_read_b32 v49, v26 offset:832
	ds_read_b32 v50, v26 offset:896
	ds_read_b32 v51, v26 offset:960
	s_waitcnt lgkmcnt(0)
	s_waitcnt vmcnt(30)
	v_lshlrev_b32_e32 v116, 16, v52
	v_and_b32_e32 v117, 0xffff0000, v52
	v_lshlrev_b32_e32 v118, 16, v53
	v_and_b32_e32 v119, 0xffff0000, v53
	v_pk_mul_f32 v[116:117], v[36:37], v[116:117] op_sel_hi:[0,1]
	v_pk_mul_f32 v[118:119], v[36:37], v[118:119] op_sel_hi:[0,1]
	v_pk_mul_f32 v[120:121], v[28:29], v[116:117]
	v_pk_mul_f32 v[122:123], v[30:31], v[118:119]
	global_store_dwordx4 v24, v[120:123], s[18:19]
	v_lshlrev_b32_e32 v116, 16, v54
	v_and_b32_e32 v117, 0xffff0000, v54
	v_lshlrev_b32_e32 v118, 16, v55
	v_and_b32_e32 v119, 0xffff0000, v55
	v_pk_mul_f32 v[116:117], v[36:37], v[116:117] op_sel_hi:[0,1]
	v_pk_mul_f32 v[118:119], v[36:37], v[118:119] op_sel_hi:[0,1]
	v_pk_mul_f32 v[124:125], v[32:33], v[116:117]
	v_pk_mul_f32 v[126:127], v[34:35], v[118:119]
	global_store_dwordx4 v24, v[124:127], s[18:19] offset:512
	s_add_u32 s18, s18, 0x20000
	s_addc_u32 s19, s19, 0
	s_waitcnt vmcnt(30)
; __device__ __forceinline__ float bf_lo(unsigned w) { return __uint_as_float(w << 16); }
; __device__ __forceinline__ float bf_hi(unsigned w) { return __uint_as_float(w & 0xffff0000u); }
; __device__ __forceinline__ void final_tiles(LAS unsigned char* lds, const bf16* XB, const float* ss, const float* g, float* OF, int G, int bx, int tid) {
;     ...
;         for (int q = 0; q < 16; ++q) {
;             const int c = tid + 512 * q, lr = c >> 5, row = u.pm * 256 + lr, col = u.pn * 256 + (c & 31) * 8;
;             const v4u w = *(const v4u*)(XB + (size_t)row * DM + col);
;             const float rs = T.tab[k * 256 + lr];
;             const f32x4 g0 = *(const f32x4*)(g + col), g1 = *(const f32x4*)(g + col + 4);
;             f32x4* o = (f32x4*)(OF + (size_t)row * DM + col);
;             o[0] = (f32x4){bf_lo(w.x) * rs * g0.x, bf_hi(w.x) * rs * g0.y, bf_lo(w.y) * rs * g0.z, bf_hi(w.y) * rs * g0.w};
;             o[1] = (f32x4){bf_lo(w.z) * rs * g1.x, bf_hi(w.z) * rs * g1.y, bf_lo(w.w) * rs * g1.z, bf_hi(w.w) * rs * g1.w};
	v_lshlrev_b32_e32 v116, 16, v56
	v_and_b32_e32 v117, 0xffff0000, v56
	v_lshlrev_b32_e32 v118, 16, v57
	v_and_b32_e32 v119, 0xffff0000, v57
	v_pk_mul_f32 v[116:117], v[36:37], v[116:117] op_sel:[1,0] op_sel_hi:[1,1]
	v_pk_mul_f32 v[118:119], v[36:37], v[118:119] op_sel:[1,0] op_sel_hi:[1,1]
	v_pk_mul_f32 v[128:129], v[28:29], v[116:117]
	v_pk_mul_f32 v[130:131], v[30:31], v[118:119]
	global_store_dwordx4 v24, v[128:131], s[18:19]
	v_lshlrev_b32_e32 v116, 16, v58
	v_and_b32_e32 v117, 0xffff0000, v58
	v_lshlrev_b32_e32 v118, 16, v59
	v_and_b32_e32 v119, 0xffff0000, v59
	v_pk_mul_f32 v[116:117], v[36:37], v[116:117] op_sel:[1,0] op_sel_hi:[1,1]
	v_pk_mul_f32 v[118:119], v[36:37], v[118:119] op_sel:[1,0] op_sel_hi:[1,1]
	v_pk_mul_f32 v[132:133], v[32:33], v[116:117]
	v_pk_mul_f32 v[134:135], v[34:35], v[118:119]
	global_store_dwordx4 v24, v[132:135], s[18:19] offset:512
	s_add_u32 s18, s18, 0x20000
	s_addc_u32 s19, s19, 0
	s_waitcnt vmcnt(30)
	v_lshlrev_b32_e32 v116, 16, v60
	v_and_b32_e32 v117, 0xffff0000, v60
	v_lshlrev_b32_e32 v118, 16, v61
	v_and_b32_e32 v119, 0xffff0000, v61
	v_pk_mul_f32 v[116:117], v[38:39], v[116:117] op_sel_hi:[0,1]
	v_pk_mul_f32 v[118:119], v[38:39], v[118:119] op_sel_hi:[0,1]
	v_pk_mul_f32 v[120:121], v[28:29], v[116:117]
	v_pk_mul_f32 v[122:123], v[30:31], v[118:119]
	global_store_dwordx4 v24, v[120:123], s[18:19]
	v_lshlrev_b32_e32 v116, 16, v62
	v_and_b32_e32 v117, 0xffff0000, v62
	v_lshlrev_b32_e32 v118, 16, v63
	v_and_b32_e32 v119, 0xffff0000, v63
	v_pk_mul_f32 v[116:117], v[38:39], v[116:117] op_sel_hi:[0,1]
	v_pk_mul_f32 v[118:119], v[38:39], v[118:119] op_sel_hi:[0,1]
	v_pk_mul_f32 v[124:125], v[32:33], v[116:117]
	v_pk_mul_f32 v[126:127], v[34:35], v[118:119]
	global_store_dwordx4 v24, v[124:127], s[18:19] offset:512
	s_add_u32 s18, s18, 0x20000
	s_addc_u32 s19, s19, 0
	s_waitcnt vmcnt(30)
	v_lshlrev_b32_e32 v116, 16, v64
	v_and_b32_e32 v117, 0xffff0000, v64
	v_lshlrev_b32_e32 v118, 16, v65
	v_and_b32_e32 v119, 0xffff0000, v65
	v_pk_mul_f32 v[116:117], v[38:39], v[116:117] op_sel:[1,0] op_sel_hi:[1,1]
	v_pk_mul_f32 v[118:119], v[38:39], v[118:119] op_sel:[1,0] op_sel_hi:[1,1]
	v_pk_mul_f32 v[128:129], v[28:29], v[116:117]
	v_pk_mul_f32 v[130:131], v[30:31], v[118:119]
	global_store_dwordx4 v24, v[128:131], s[18:19]
	v_lshlrev_b32_e32 v116, 16, v66
	v_and_b32_e32 v117, 0xffff0000, v66
	v_lshlrev_b32_e32 v118, 16, v67
	v_and_b32_e32 v119, 0xffff0000, v67
	v_pk_mul_f32 v[116:117], v[38:39], v[116:117] op_sel:[1,0] op_sel_hi:[1,1]
	v_pk_mul_f32 v[118:119], v[38:39], v[118:119] op_sel:[1,0] op_sel_hi:[1,1]
	v_pk_mul_f32 v[132:133], v[32:33], v[116:117]
	v_pk_mul_f32 v[134:135], v[34:35], v[118:119]
	global_store_dwordx4 v24, v[132:135], s[18:19] offset:512
	s_add_u32 s18, s18, 0x20000
	s_addc_u32 s19, s19, 0
	s_waitcnt vmcnt(30)
	v_lshlrev_b32_e32 v116, 16, v68
	v_and_b32_e32 v117, 0xffff0000, v68
	v_lshlrev_b32_e32 v118, 16, v69
	v_and_b32_e32 v119, 0xffff0000, v69
	v_pk_mul_f32 v[116:117], v[40:41], v[116:117] op_sel_hi:[0,1]
	v_pk_mul_f32 v[118:119], v[40:41], v[118:119] op_sel_hi:[0,1]
	v_pk_mul_f32 v[120:121], v[28:29], v[116:117]
	v_pk_mul_f32 v[122:123], v[30:31], v[118:119]
	global_store_dwordx4 v24, v[120:123], s[18:19]
	v_lshlrev_b32_e32 v116, 16, v70
	v_and_b32_e32 v117, 0xffff0000, v70
	v_lshlrev_b32_e32 v118, 16, v71
	v_and_b32_e32 v119, 0xffff0000, v71
	v_pk_mul_f32 v[116:117], v[40:41], v[116:117] op_sel_hi:[0,1]
	v_pk_mul_f32 v[118:119], v[40:41], v[118:119] op_sel_hi:[0,1]
	v_pk_mul_f32 v[124:125], v[32:33], v[116:117]
	v_pk_mul_f32 v[126:127], v[34:35], v[118:119]
	global_store_dwordx4 v24, v[124:127], s[18:19] offset:512
	s_add_u32 s18, s18, 0x20000
	s_addc_u32 s19, s19, 0
	s_waitcnt vmcnt(30)
	v_lshlrev_b32_e32 v116, 16, v72
	v_and_b32_e32 v117, 0xffff0000, v72
	v_lshlrev_b32_e32 v118, 16, v73
	v_and_b32_e32 v119, 0xffff0000, v73
	v_pk_mul_f32 v[116:117], v[40:41], v[116:117] op_sel:[1,0] op_sel_hi:[1,1]
	v_pk_mul_f32 v[118:119], v[40:41], v[118:119] op_sel:[1,0] op_sel_hi:[1,1]
	v_pk_mul_f32 v[128:129], v[28:29], v[116:117]
	v_pk_mul_f32 v[130:131], v[30:31], v[118:119]
	global_store_dwordx4 v24, v[128:131], s[18:19]
	v_lshlrev_b32_e32 v116, 16, v74
	v_and_b32_e32 v117, 0xffff0000, v74
	v_lshlrev_b32_e32 v118, 16, v75
	v_and_b32_e32 v119, 0xffff0000, v75
	v_pk_mul_f32 v[116:117], v[40:41], v[116:117] op_sel:[1,0] op_sel_hi:[1,1]
	v_pk_mul_f32 v[118:119], v[40:41], v[118:119] op_sel:[1,0] op_sel_hi:[1,1]
	v_pk_mul_f32 v[132:133], v[32:33], v[116:117]
	v_pk_mul_f32 v[134:135], v[34:35], v[118:119]
	global_store_dwordx4 v24, v[132:135], s[18:19] offset:512
	s_add_u32 s18, s18, 0x20000
	s_addc_u32 s19, s19, 0
	s_waitcnt vmcnt(30)
	v_lshlrev_b32_e32 v116, 16, v76
	v_and_b32_e32 v117, 0xffff0000, v76
	v_lshlrev_b32_e32 v118, 16, v77
	v_and_b32_e32 v119, 0xffff0000, v77
	v_pk_mul_f32 v[116:117], v[42:43], v[116:117] op_sel_hi:[0,1]
	v_pk_mul_f32 v[118:119], v[42:43], v[118:119] op_sel_hi:[0,1]
	v_pk_mul_f32 v[120:121], v[28:29], v[116:117]
	v_pk_mul_f32 v[122:123], v[30:31], v[118:119]
	global_store_dwordx4 v24, v[120:123], s[18:19]
	v_lshlrev_b32_e32 v116, 16, v78
	v_and_b32_e32 v117, 0xffff0000, v78
	v_lshlrev_b32_e32 v118, 16, v79
	v_and_b32_e32 v119, 0xffff0000, v79
	v_pk_mul_f32 v[116:117], v[42:43], v[116:117] op_sel_hi:[0,1]
	v_pk_mul_f32 v[118:119], v[42:43], v[118:119] op_sel_hi:[0,1]
	v_pk_mul_f32 v[124:125], v[32:33], v[116:117]
	v_pk_mul_f32 v[126:127], v[34:35], v[118:119]
	global_store_dwordx4 v24, v[124:127], s[18:19] offset:512
	s_add_u32 s18, s18, 0x20000
	s_addc_u32 s19, s19, 0
	s_waitcnt vmcnt(30)
; __device__ __forceinline__ float bf_lo(unsigned w) { return __uint_as_float(w << 16); }
; __device__ __forceinline__ float bf_hi(unsigned w) { return __uint_as_float(w & 0xffff0000u); }
; __device__ __forceinline__ void final_tiles(LAS unsigned char* lds, const bf16* XB, const float* ss, const float* g, float* OF, int G, int bx, int tid) {
;     ...
;         for (int q = 0; q < 16; ++q) {
;             const int c = tid + 512 * q, lr = c >> 5, row = u.pm * 256 + lr, col = u.pn * 256 + (c & 31) * 8;
;             const v4u w = *(const v4u*)(XB + (size_t)row * DM + col);
;             const float rs = T.tab[k * 256 + lr];
;             const f32x4 g0 = *(const f32x4*)(g + col), g1 = *(const f32x4*)(g + col + 4);
;             f32x4* o = (f32x4*)(OF + (size_t)row * DM + col);
;             o[0] = (f32x4){bf_lo(w.x) * rs * g0.x, bf_hi(w.x) * rs * g0.y, bf_lo(w.y) * rs * g0.z, bf_hi(w.y) * rs * g0.w};
;             o[1] = (f32x4){bf_lo(w.z) * rs * g1.x, bf_hi(w.z) * rs * g1.y, bf_lo(w.w) * rs * g1.z, bf_hi(w.w) * rs * g1.w};
	v_lshlrev_b32_e32 v116, 16, v80
	v_and_b32_e32 v117, 0xffff0000, v80
	v_lshlrev_b32_e32 v118, 16, v81
	v_and_b32_e32 v119, 0xffff0000, v81
	v_pk_mul_f32 v[116:117], v[42:43], v[116:117] op_sel:[1,0] op_sel_hi:[1,1]
	v_pk_mul_f32 v[118:119], v[42:43], v[118:119] op_sel:[1,0] op_sel_hi:[1,1]
	v_pk_mul_f32 v[128:129], v[28:29], v[116:117]
	v_pk_mul_f32 v[130:131], v[30:31], v[118:119]
	global_store_dwordx4 v24, v[128:131], s[18:19]
	v_lshlrev_b32_e32 v116, 16, v82
	v_and_b32_e32 v117, 0xffff0000, v82
	v_lshlrev_b32_e32 v118, 16, v83
	v_and_b32_e32 v119, 0xffff0000, v83
	v_pk_mul_f32 v[116:117], v[42:43], v[116:117] op_sel:[1,0] op_sel_hi:[1,1]
	v_pk_mul_f32 v[118:119], v[42:43], v[118:119] op_sel:[1,0] op_sel_hi:[1,1]
	v_pk_mul_f32 v[132:133], v[32:33], v[116:117]
	v_pk_mul_f32 v[134:135], v[34:35], v[118:119]
	global_store_dwordx4 v24, v[132:135], s[18:19] offset:512
	s_add_u32 s18, s18, 0x20000
	s_addc_u32 s19, s19, 0
	s_waitcnt vmcnt(30)
	v_lshlrev_b32_e32 v116, 16, v84
	v_and_b32_e32 v117, 0xffff0000, v84
	v_lshlrev_b32_e32 v118, 16, v85
	v_and_b32_e32 v119, 0xffff0000, v85
	v_pk_mul_f32 v[116:117], v[44:45], v[116:117] op_sel_hi:[0,1]
	v_pk_mul_f32 v[118:119], v[44:45], v[118:119] op_sel_hi:[0,1]
	v_pk_mul_f32 v[120:121], v[28:29], v[116:117]
	v_pk_mul_f32 v[122:123], v[30:31], v[118:119]
	global_store_dwordx4 v24, v[120:123], s[18:19]
	v_lshlrev_b32_e32 v116, 16, v86
	v_and_b32_e32 v117, 0xffff0000, v86
	v_lshlrev_b32_e32 v118, 16, v87
	v_and_b32_e32 v119, 0xffff0000, v87
	v_pk_mul_f32 v[116:117], v[44:45], v[116:117] op_sel_hi:[0,1]
	v_pk_mul_f32 v[118:119], v[44:45], v[118:119] op_sel_hi:[0,1]
	v_pk_mul_f32 v[124:125], v[32:33], v[116:117]
	v_pk_mul_f32 v[126:127], v[34:35], v[118:119]
	global_store_dwordx4 v24, v[124:127], s[18:19] offset:512
	s_add_u32 s18, s18, 0x20000
	s_addc_u32 s19, s19, 0
	s_waitcnt vmcnt(30)
	v_lshlrev_b32_e32 v116, 16, v88
	v_and_b32_e32 v117, 0xffff0000, v88
	v_lshlrev_b32_e32 v118, 16, v89
	v_and_b32_e32 v119, 0xffff0000, v89
	v_pk_mul_f32 v[116:117], v[44:45], v[116:117] op_sel:[1,0] op_sel_hi:[1,1]
	v_pk_mul_f32 v[118:119], v[44:45], v[118:119] op_sel:[1,0] op_sel_hi:[1,1]
	v_pk_mul_f32 v[128:129], v[28:29], v[116:117]
	v_pk_mul_f32 v[130:131], v[30:31], v[118:119]
	global_store_dwordx4 v24, v[128:131], s[18:19]
	v_lshlrev_b32_e32 v116, 16, v90
	v_and_b32_e32 v117, 0xffff0000, v90
	v_lshlrev_b32_e32 v118, 16, v91
	v_and_b32_e32 v119, 0xffff0000, v91
	v_pk_mul_f32 v[116:117], v[44:45], v[116:117] op_sel:[1,0] op_sel_hi:[1,1]
	v_pk_mul_f32 v[118:119], v[44:45], v[118:119] op_sel:[1,0] op_sel_hi:[1,1]
	v_pk_mul_f32 v[132:133], v[32:33], v[116:117]
	v_pk_mul_f32 v[134:135], v[34:35], v[118:119]
	global_store_dwordx4 v24, v[132:135], s[18:19] offset:512
	s_add_u32 s18, s18, 0x20000
	s_addc_u32 s19, s19, 0
	s_waitcnt vmcnt(30)
	v_lshlrev_b32_e32 v116, 16, v92
	v_and_b32_e32 v117, 0xffff0000, v92
	v_lshlrev_b32_e32 v118, 16, v93
	v_and_b32_e32 v119, 0xffff0000, v93
	v_pk_mul_f32 v[116:117], v[46:47], v[116:117] op_sel_hi:[0,1]
	v_pk_mul_f32 v[118:119], v[46:47], v[118:119] op_sel_hi:[0,1]
	v_pk_mul_f32 v[120:121], v[28:29], v[116:117]
	v_pk_mul_f32 v[122:123], v[30:31], v[118:119]
	global_store_dwordx4 v24, v[120:123], s[18:19]
	v_lshlrev_b32_e32 v116, 16, v94
	v_and_b32_e32 v117, 0xffff0000, v94
	v_lshlrev_b32_e32 v118, 16, v95
	v_and_b32_e32 v119, 0xffff0000, v95
	v_pk_mul_f32 v[116:117], v[46:47], v[116:117] op_sel_hi:[0,1]
	v_pk_mul_f32 v[118:119], v[46:47], v[118:119] op_sel_hi:[0,1]
	v_pk_mul_f32 v[124:125], v[32:33], v[116:117]
	v_pk_mul_f32 v[126:127], v[34:35], v[118:119]
	global_store_dwordx4 v24, v[124:127], s[18:19] offset:512
	s_add_u32 s18, s18, 0x20000
	s_addc_u32 s19, s19, 0
	s_waitcnt vmcnt(30)
	v_lshlrev_b32_e32 v116, 16, v96
	v_and_b32_e32 v117, 0xffff0000, v96
	v_lshlrev_b32_e32 v118, 16, v97
	v_and_b32_e32 v119, 0xffff0000, v97
	v_pk_mul_f32 v[116:117], v[46:47], v[116:117] op_sel:[1,0] op_sel_hi:[1,1]
	v_pk_mul_f32 v[118:119], v[46:47], v[118:119] op_sel:[1,0] op_sel_hi:[1,1]
	v_pk_mul_f32 v[128:129], v[28:29], v[116:117]
	v_pk_mul_f32 v[130:131], v[30:31], v[118:119]
	global_store_dwordx4 v24, v[128:131], s[18:19]
	v_lshlrev_b32_e32 v116, 16, v98
	v_and_b32_e32 v117, 0xffff0000, v98
	v_lshlrev_b32_e32 v118, 16, v99
	v_and_b32_e32 v119, 0xffff0000, v99
	v_pk_mul_f32 v[116:117], v[46:47], v[116:117] op_sel:[1,0] op_sel_hi:[1,1]
	v_pk_mul_f32 v[118:119], v[46:47], v[118:119] op_sel:[1,0] op_sel_hi:[1,1]
	v_pk_mul_f32 v[132:133], v[32:33], v[116:117]
	v_pk_mul_f32 v[134:135], v[34:35], v[118:119]
	global_store_dwordx4 v24, v[132:135], s[18:19] offset:512
	s_add_u32 s18, s18, 0x20000
	s_addc_u32 s19, s19, 0
	s_waitcnt vmcnt(30)
; __device__ __forceinline__ float bf_lo(unsigned w) { return __uint_as_float(w << 16); }
; __device__ __forceinline__ float bf_hi(unsigned w) { return __uint_as_float(w & 0xffff0000u); }
; __device__ __forceinline__ void final_tiles(LAS unsigned char* lds, const bf16* XB, const float* ss, const float* g, float* OF, int G, int bx, int tid) {
;     ...
;         for (int q = 0; q < 16; ++q) {
;             const int c = tid + 512 * q, lr = c >> 5, row = u.pm * 256 + lr, col = u.pn * 256 + (c & 31) * 8;
;             const v4u w = *(const v4u*)(XB + (size_t)row * DM + col);
;             const float rs = T.tab[k * 256 + lr];
;             const f32x4 g0 = *(const f32x4*)(g + col), g1 = *(const f32x4*)(g + col + 4);
;             f32x4* o = (f32x4*)(OF + (size_t)row * DM + col);
;             o[0] = (f32x4){bf_lo(w.x) * rs * g0.x, bf_hi(w.x) * rs * g0.y, bf_lo(w.y) * rs * g0.z, bf_hi(w.y) * rs * g0.w};
;             o[1] = (f32x4){bf_lo(w.z) * rs * g1.x, bf_hi(w.z) * rs * g1.y, bf_lo(w.w) * rs * g1.z, bf_hi(w.w) * rs * g1.w};
;         }
;     }
	v_lshlrev_b32_e32 v116, 16, v100
	v_and_b32_e32 v117, 0xffff0000, v100
	v_lshlrev_b32_e32 v118, 16, v101
	v_and_b32_e32 v119, 0xffff0000, v101
	v_pk_mul_f32 v[116:117], v[48:49], v[116:117] op_sel_hi:[0,1]
	v_pk_mul_f32 v[118:119], v[48:49], v[118:119] op_sel_hi:[0,1]
	v_pk_mul_f32 v[120:121], v[28:29], v[116:117]
	v_pk_mul_f32 v[122:123], v[30:31], v[118:119]
	global_store_dwordx4 v24, v[120:123], s[18:19]
	v_lshlrev_b32_e32 v116, 16, v102
	v_and_b32_e32 v117, 0xffff0000, v102
	v_lshlrev_b32_e32 v118, 16, v103
	v_and_b32_e32 v119, 0xffff0000, v103
	v_pk_mul_f32 v[116:117], v[48:49], v[116:117] op_sel_hi:[0,1]
	v_pk_mul_f32 v[118:119], v[48:49], v[118:119] op_sel_hi:[0,1]
	v_pk_mul_f32 v[124:125], v[32:33], v[116:117]
	v_pk_mul_f32 v[126:127], v[34:35], v[118:119]
	global_store_dwordx4 v24, v[124:127], s[18:19] offset:512
	s_add_u32 s18, s18, 0x20000
	s_addc_u32 s19, s19, 0
	s_waitcnt vmcnt(30)
	v_lshlrev_b32_e32 v116, 16, v104
	v_and_b32_e32 v117, 0xffff0000, v104
	v_lshlrev_b32_e32 v118, 16, v105
	v_and_b32_e32 v119, 0xffff0000, v105
	v_pk_mul_f32 v[116:117], v[48:49], v[116:117] op_sel:[1,0] op_sel_hi:[1,1]
	v_pk_mul_f32 v[118:119], v[48:49], v[118:119] op_sel:[1,0] op_sel_hi:[1,1]
	v_pk_mul_f32 v[128:129], v[28:29], v[116:117]
	v_pk_mul_f32 v[130:131], v[30:31], v[118:119]
	global_store_dwordx4 v24, v[128:131], s[18:19]
	v_lshlrev_b32_e32 v116, 16, v106
	v_and_b32_e32 v117, 0xffff0000, v106
	v_lshlrev_b32_e32 v118, 16, v107
	v_and_b32_e32 v119, 0xffff0000, v107
	v_pk_mul_f32 v[116:117], v[48:49], v[116:117] op_sel:[1,0] op_sel_hi:[1,1]
	v_pk_mul_f32 v[118:119], v[48:49], v[118:119] op_sel:[1,0] op_sel_hi:[1,1]
	v_pk_mul_f32 v[132:133], v[32:33], v[116:117]
	v_pk_mul_f32 v[134:135], v[34:35], v[118:119]
	global_store_dwordx4 v24, v[132:135], s[18:19] offset:512
	s_add_u32 s18, s18, 0x20000
	s_addc_u32 s19, s19, 0
	s_waitcnt vmcnt(30)
	v_lshlrev_b32_e32 v116, 16, v108
	v_and_b32_e32 v117, 0xffff0000, v108
	v_lshlrev_b32_e32 v118, 16, v109
	v_and_b32_e32 v119, 0xffff0000, v109
	v_pk_mul_f32 v[116:117], v[50:51], v[116:117] op_sel_hi:[0,1]
	v_pk_mul_f32 v[118:119], v[50:51], v[118:119] op_sel_hi:[0,1]
	v_pk_mul_f32 v[120:121], v[28:29], v[116:117]
	v_pk_mul_f32 v[122:123], v[30:31], v[118:119]
	global_store_dwordx4 v24, v[120:123], s[18:19]
	v_lshlrev_b32_e32 v116, 16, v110
	v_and_b32_e32 v117, 0xffff0000, v110
	v_lshlrev_b32_e32 v118, 16, v111
	v_and_b32_e32 v119, 0xffff0000, v111
	v_pk_mul_f32 v[116:117], v[50:51], v[116:117] op_sel_hi:[0,1]
	v_pk_mul_f32 v[118:119], v[50:51], v[118:119] op_sel_hi:[0,1]
	v_pk_mul_f32 v[124:125], v[32:33], v[116:117]
	v_pk_mul_f32 v[126:127], v[34:35], v[118:119]
	global_store_dwordx4 v24, v[124:127], s[18:19] offset:512
	s_add_u32 s18, s18, 0x20000
	s_addc_u32 s19, s19, 0
	s_waitcnt vmcnt(30)
	v_lshlrev_b32_e32 v116, 16, v112
	v_and_b32_e32 v117, 0xffff0000, v112
	v_lshlrev_b32_e32 v118, 16, v113
	v_and_b32_e32 v119, 0xffff0000, v113
	v_pk_mul_f32 v[116:117], v[50:51], v[116:117] op_sel:[1,0] op_sel_hi:[1,1]
	v_pk_mul_f32 v[118:119], v[50:51], v[118:119] op_sel:[1,0] op_sel_hi:[1,1]
	v_pk_mul_f32 v[128:129], v[28:29], v[116:117]
	v_pk_mul_f32 v[130:131], v[30:31], v[118:119]
	global_store_dwordx4 v24, v[128:131], s[18:19]
	v_lshlrev_b32_e32 v116, 16, v114
	v_and_b32_e32 v117, 0xffff0000, v114
	v_lshlrev_b32_e32 v118, 16, v115
	v_and_b32_e32 v119, 0xffff0000, v115
	v_pk_mul_f32 v[116:117], v[50:51], v[116:117] op_sel:[1,0] op_sel_hi:[1,1]
	v_pk_mul_f32 v[118:119], v[50:51], v[118:119] op_sel:[1,0] op_sel_hi:[1,1]
	v_pk_mul_f32 v[132:133], v[32:33], v[116:117]
	v_pk_mul_f32 v[134:135], v[34:35], v[118:119]
	global_store_dwordx4 v24, v[132:135], s[18:19] offset:512
	s_add_i32 s8, s8, 1
	s_mov_b64 s[0:1], 0
	s_branch .LBB0_643
